# v32: v25 + one early L2 write-back per XCC (by the block arriving 8 places before the last) at barriers that need a write-back
# baseline (speedup 1.0000x reference)
.Lxb0_go:
	v_add_u32_e32 v249, 1, v244
	ds_write_b32 v241, v249 offset:8
	v_sub_u32_e32 v255, v249, v245
	v_mul_lo_u32 v250, v255, v242
	v_mul_lo_u32 v251, v255, v243
	v_add_u32_e32 v253, 0x2400, v254
	v_mov_b32_e32 v252, 0
	s_waitcnt vmcnt(0)
	buffer_inv sc1
	v_add_u32_e32 v248, 1, v248
	v_cmp_eq_u32_e32 vcc, v248, v250
	s_cbranch_vccnz .Lxb0_lead
	v_sub_u32_e32 v255, v250, v248
	v_cmp_eq_u32_e32 vcc, 8, v255
	s_cbranch_vccz .Lxb0_wait
	buffer_wbl2 sc1
	s_branch .Lxb0_wait
.Lxb0_lead:
	buffer_wbl2 sc1
	s_waitcnt vmcnt(0)
	v_mov_b32_e32 v246, 0x3400
	global_atomic_add v248, v246, v247, s[60:61] sc0
	s_waitcnt vmcnt(0)
	v_add_u32_e32 v248, 1, v248
	v_cmp_ge_u32_e32 vcc, v248, v251
	s_cbranch_vccz .Lxb0_wait
	v_mov_b32_e32 v246, 0x2400
	global_atomic_add v246, v247, s[60:61]
	global_atomic_add v246, v247, s[60:61] offset:256
	global_atomic_add v246, v247, s[60:61] offset:512
	global_atomic_add v246, v247, s[60:61] offset:768
	global_atomic_add v246, v247, s[60:61] offset:1024
	global_atomic_add v246, v247, s[60:61] offset:1280
	global_atomic_add v246, v247, s[60:61] offset:1536
	global_atomic_add v246, v247, s[60:61] offset:1792
	global_atomic_add v246, v247, s[60:61] offset:2048
	global_atomic_add v246, v247, s[60:61] offset:2304
	global_atomic_add v246, v247, s[60:61] offset:2560
	global_atomic_add v246, v247, s[60:61] offset:2816
	global_atomic_add v246, v247, s[60:61] offset:3072
	global_atomic_add v246, v247, s[60:61] offset:3328
	global_atomic_add v246, v247, s[60:61] offset:3584
	global_atomic_add v246, v247, s[60:61] offset:3840
	s_branch .Lxb0_done
